# speedup vs baseline: 1.0168x; 1.0025x over previous
; __device__ __forceinline__ u16 f2bf(float f) { return (u16)cvtpk(f, f); }
; __device__ __forceinline__ float siluf_(float x) { return x * __builtin_amdgcn_rcpf(1.f + __expf(-x)); }
; __device__ __forceinline__ void phase_ffn_in(const Params& p, int L, int f, char* lds) {
;     ...
;   auto epi_ffn = [&](int m0, int n0, auto& acc) {
;       constexpr int MIx = sizeof(acc) / sizeof(acc[0]);
;       EPI_IDX
; #pragma unroll
;       for (int mi = 0; mi < MIx; ++mi)
; #pragma unroll
;         for (int np = 0; np < 2; ++np) {
;           const int c = (((n0 + wn * 64) >> 5) + np) * 16 + l15;
; #pragma unroll
;           for (int j = 0; j < 4; ++j) {
;             const int row = m0 + wm * (MIx * 16) + mi * 16 + quad * 4 + j;
;             float a = acc[mi][2 * np][j], g = acc[mi][2 * np + 1][j];
;             hid[(size_t)row * DFF + c] = f2bf(siluf_(a) * g);
;           }
;         }
;     };
.LBB0_206:
	s_mul_hi_i32 s9, s7, 0x2e8ba2e9
	s_lshr_b32 s62, s9, 31
	s_ashr_i32 s9, s9, 4
	s_add_i32 s9, s9, s62
	s_ashr_i32 s62, s7, 31
	s_lshr_b32 s62, s62, 30
	s_add_i32 s62, s7, s62
	s_and_b32 s62, s62, 0xfffffc
	s_sub_i32 s62, s7, s62
	s_lshl_b32 s63, s9, 10
	s_lshl_b32 s62, s62, 8
	v_mov_b32 v140, v200
	v_mov_b32 v128, v200
	s_add_i32 s63, s63, s62
	v_and_b32_e32 v141, 0xc0, v128
	v_ashrrev_i32_e32 v128, 1, v128
	v_lshrrev_b32_e32 v146, 2, v140
	v_and_b32_e32 v128, 0xffffff80, v128
	v_and_or_b32 v146, v146, 12, s63
	v_add_u32_e32 v128, v146, v128
	s_mulk_i32 s9, 0x58
	s_sub_i32 s9, s7, s9
	s_bfe_i32 s62, s9, 0x80000
	s_bfe_u32 s62, s62, 0x2000d
	s_add_i32 s9, s9, s62
	s_bfe_i32 s9, s9, 0x80000
	s_sext_i32_i16 s9, s9
	s_lshl_b32 s9, s9, 6
	s_and_b32 s9, s9, 0xffffff00
	v_or_b32_e32 v141, s9, v141
	v_ashrrev_i32_e32 v141, 1, v141
	v_and_or_b32 v140, v140, 15, v141
	v_readlane_b32 s16, v254, 15
	v_ashrrev_i32_e32 v141, 31, v140
	v_readlane_b32 s17, v254, 16
	s_nop 1
	v_lshl_add_u64 v[140:141], v[140:141], 1, s[16:17]
	s_add_i32 s7, s7, s33
	s_cmpk_gt_i32 s7, 0xaff
	v_and_b32_e32 v147, 1, v200
	v_add_u32_e32 v148, v128, v147
	v_lshlrev_b32_e32 v149, 1, v147
	v_sub_co_u32_e32 v150, vcc, v140, v149
	s_nop 1
	v_subbrev_co_u32_e32 v151, vcc, 0, v141, vcc
	v_mov_b32_e32 v152, 0x5040100
	v_mov_b32_e32 v153, 0x3020706
	v_cmp_eq_u32_e32 vcc, 1, v147
	s_nop 1
	v_cndmask_b32_e32 v152, v152, v153, vcc
	v_mov_b32_e32 v154, v148
	v_mad_i64_i32 v[156:157], s[62:63], v154, s96, v[150:151]
	v_mul_f32_e32 v160, 0xbfb8aa3b, v124
	v_mul_f32_e32 v161, 0xbfb8aa3b, v125
	v_mul_f32_e32 v162, 0xbfb8aa3b, v116
	v_mul_f32_e32 v163, 0xbfb8aa3b, v117
	v_exp_f32_e32 v160, v160
	v_exp_f32_e32 v161, v161
	v_exp_f32_e32 v162, v162
	v_exp_f32_e32 v163, v163
	v_add_f32_e32 v160, 1.0, v160
	v_add_f32_e32 v161, 1.0, v161
	v_add_f32_e32 v162, 1.0, v162
	v_add_f32_e32 v163, 1.0, v163
	v_rcp_f32_e32 v160, v160
	v_rcp_f32_e32 v161, v161
	v_rcp_f32_e32 v162, v162
	v_rcp_f32_e32 v163, v163
	v_mul_f32_e32 v160, v124, v160
	v_mul_f32_e32 v161, v125, v161
	v_mul_f32_e32 v162, v116, v162
	v_mul_f32_e32 v163, v117, v163
	v_mul_f32_e32 v160, v120, v160
	v_mul_f32_e32 v161, v121, v161
	v_mul_f32_e32 v162, v112, v162
	v_mul_f32_e32 v163, v113, v163
	v_cvt_pk_bf16_f32 v164, v160, v161
	v_cvt_pk_bf16_f32 v165, v162, v163
	s_nop 0
	v_mov_b32_dpp v166, v164 quad_perm:[1,0,3,2] row_mask:0xf bank_mask:0xf
	v_mov_b32_dpp v167, v165 quad_perm:[1,0,3,2] row_mask:0xf bank_mask:0xf
	v_perm_b32 v168, v166, v164, v152
	v_perm_b32 v169, v167, v165, v152
	global_store_dword v[156:157], v168, off
	global_store_dword v[156:157], v169, off offset:32
	v_add_u32_e32 v154, 2, v148
	v_mad_i64_i32 v[156:157], s[62:63], v154, s96, v[150:151]
	v_mul_f32_e32 v160, 0xbfb8aa3b, v126
	v_mul_f32_e32 v161, 0xbfb8aa3b, v127
	v_mul_f32_e32 v162, 0xbfb8aa3b, v118
	v_mul_f32_e32 v163, 0xbfb8aa3b, v119
	v_exp_f32_e32 v160, v160
	v_exp_f32_e32 v161, v161
	v_exp_f32_e32 v162, v162
	v_exp_f32_e32 v163, v163
	v_add_f32_e32 v160, 1.0, v160
	v_add_f32_e32 v161, 1.0, v161
	v_add_f32_e32 v162, 1.0, v162
	v_add_f32_e32 v163, 1.0, v163
	v_rcp_f32_e32 v160, v160
	v_rcp_f32_e32 v161, v161
	v_rcp_f32_e32 v162, v162
	v_rcp_f32_e32 v163, v163
	v_mul_f32_e32 v160, v126, v160
	v_mul_f32_e32 v161, v127, v161
	v_mul_f32_e32 v162, v118, v162
	v_mul_f32_e32 v163, v119, v163
	v_mul_f32_e32 v160, v122, v160
	v_mul_f32_e32 v161, v123, v161
	v_mul_f32_e32 v162, v114, v162
	v_mul_f32_e32 v163, v115, v163
	v_cvt_pk_bf16_f32 v164, v160, v161
	v_cvt_pk_bf16_f32 v165, v162, v163
	s_nop 0
	v_mov_b32_dpp v166, v164 quad_perm:[1,0,3,2] row_mask:0xf bank_mask:0xf
	v_mov_b32_dpp v167, v165 quad_perm:[1,0,3,2] row_mask:0xf bank_mask:0xf
	v_perm_b32 v168, v166, v164, v152
	v_perm_b32 v169, v167, v165, v152
	global_store_dword v[156:157], v168, off
	global_store_dword v[156:157], v169, off offset:32
	v_add_u32_e32 v154, 16, v148
	v_mad_i64_i32 v[156:157], s[62:63], v154, s96, v[150:151]
	v_mul_f32_e32 v160, 0xbfb8aa3b, v108
	v_mul_f32_e32 v161, 0xbfb8aa3b, v109
	v_mul_f32_e32 v162, 0xbfb8aa3b, v100
	v_mul_f32_e32 v163, 0xbfb8aa3b, v101
	v_exp_f32_e32 v160, v160
	v_exp_f32_e32 v161, v161
	v_exp_f32_e32 v162, v162
	v_exp_f32_e32 v163, v163
	v_add_f32_e32 v160, 1.0, v160
	v_add_f32_e32 v161, 1.0, v161
	v_add_f32_e32 v162, 1.0, v162
	v_add_f32_e32 v163, 1.0, v163
	v_rcp_f32_e32 v160, v160
	v_rcp_f32_e32 v161, v161
	v_rcp_f32_e32 v162, v162
	v_rcp_f32_e32 v163, v163
	v_mul_f32_e32 v160, v108, v160
	v_mul_f32_e32 v161, v109, v161
	v_mul_f32_e32 v162, v100, v162
	v_mul_f32_e32 v163, v101, v163
	v_mul_f32_e32 v160, v104, v160
	v_mul_f32_e32 v161, v105, v161
	v_mul_f32_e32 v162, v96, v162
	v_mul_f32_e32 v163, v97, v163
	v_cvt_pk_bf16_f32 v164, v160, v161
	v_cvt_pk_bf16_f32 v165, v162, v163
	s_nop 0
	v_mov_b32_dpp v166, v164 quad_perm:[1,0,3,2] row_mask:0xf bank_mask:0xf
	v_mov_b32_dpp v167, v165 quad_perm:[1,0,3,2] row_mask:0xf bank_mask:0xf
	v_perm_b32 v168, v166, v164, v152
	v_perm_b32 v169, v167, v165, v152
	global_store_dword v[156:157], v168, off
	global_store_dword v[156:157], v169, off offset:32
	v_add_u32_e32 v154, 18, v148
	v_mad_i64_i32 v[156:157], s[62:63], v154, s96, v[150:151]
	v_mul_f32_e32 v160, 0xbfb8aa3b, v110
	v_mul_f32_e32 v161, 0xbfb8aa3b, v111
	v_mul_f32_e32 v162, 0xbfb8aa3b, v102
	v_mul_f32_e32 v163, 0xbfb8aa3b, v103
	v_exp_f32_e32 v160, v160
	v_exp_f32_e32 v161, v161
	v_exp_f32_e32 v162, v162
	v_exp_f32_e32 v163, v163
	v_add_f32_e32 v160, 1.0, v160
	v_add_f32_e32 v161, 1.0, v161
	v_add_f32_e32 v162, 1.0, v162
	v_add_f32_e32 v163, 1.0, v163
	v_rcp_f32_e32 v160, v160
	v_rcp_f32_e32 v161, v161
	v_rcp_f32_e32 v162, v162
	v_rcp_f32_e32 v163, v163
; __device__ __forceinline__ u16 f2bf(float f) { return (u16)cvtpk(f, f); }
; __device__ __forceinline__ float siluf_(float x) { return x * __builtin_amdgcn_rcpf(1.f + __expf(-x)); }
; __device__ __forceinline__ void phase_ffn_in(const Params& p, int L, int f, char* lds) {
;     ...
;   auto epi_ffn = [&](int m0, int n0, auto& acc) {
;       constexpr int MIx = sizeof(acc) / sizeof(acc[0]);
;       EPI_IDX
; #pragma unroll
;       for (int mi = 0; mi < MIx; ++mi)
; #pragma unroll
;         for (int np = 0; np < 2; ++np) {
;           const int c = (((n0 + wn * 64) >> 5) + np) * 16 + l15;
; #pragma unroll
;           for (int j = 0; j < 4; ++j) {
;             const int row = m0 + wm * (MIx * 16) + mi * 16 + quad * 4 + j;
;             float a = acc[mi][2 * np][j], g = acc[mi][2 * np + 1][j];
;             hid[(size_t)row * DFF + c] = f2bf(siluf_(a) * g);
;           }
;         }
;     };
	v_mul_f32_e32 v160, v110, v160
	v_mul_f32_e32 v161, v111, v161
	v_mul_f32_e32 v162, v102, v162
	v_mul_f32_e32 v163, v103, v163
	v_mul_f32_e32 v160, v106, v160
	v_mul_f32_e32 v161, v107, v161
	v_mul_f32_e32 v162, v98, v162
	v_mul_f32_e32 v163, v99, v163
	v_cvt_pk_bf16_f32 v164, v160, v161
	v_cvt_pk_bf16_f32 v165, v162, v163
	s_nop 0
	v_mov_b32_dpp v166, v164 quad_perm:[1,0,3,2] row_mask:0xf bank_mask:0xf
	v_mov_b32_dpp v167, v165 quad_perm:[1,0,3,2] row_mask:0xf bank_mask:0xf
	v_perm_b32 v168, v166, v164, v152
	v_perm_b32 v169, v167, v165, v152
	global_store_dword v[156:157], v168, off
	global_store_dword v[156:157], v169, off offset:32
	v_add_u32_e32 v154, 32, v148
	v_mad_i64_i32 v[156:157], s[62:63], v154, s96, v[150:151]
	v_mul_f32_e32 v160, 0xbfb8aa3b, v92
	v_mul_f32_e32 v161, 0xbfb8aa3b, v93
	v_mul_f32_e32 v162, 0xbfb8aa3b, v84
	v_mul_f32_e32 v163, 0xbfb8aa3b, v85
	v_exp_f32_e32 v160, v160
	v_exp_f32_e32 v161, v161
	v_exp_f32_e32 v162, v162
	v_exp_f32_e32 v163, v163
	v_add_f32_e32 v160, 1.0, v160
	v_add_f32_e32 v161, 1.0, v161
	v_add_f32_e32 v162, 1.0, v162
	v_add_f32_e32 v163, 1.0, v163
	v_rcp_f32_e32 v160, v160
	v_rcp_f32_e32 v161, v161
	v_rcp_f32_e32 v162, v162
	v_rcp_f32_e32 v163, v163
	v_mul_f32_e32 v160, v92, v160
	v_mul_f32_e32 v161, v93, v161
	v_mul_f32_e32 v162, v84, v162
	v_mul_f32_e32 v163, v85, v163
	v_mul_f32_e32 v160, v88, v160
	v_mul_f32_e32 v161, v89, v161
	v_mul_f32_e32 v162, v80, v162
	v_mul_f32_e32 v163, v81, v163
	v_cvt_pk_bf16_f32 v164, v160, v161
	v_cvt_pk_bf16_f32 v165, v162, v163
	s_nop 0
	v_mov_b32_dpp v166, v164 quad_perm:[1,0,3,2] row_mask:0xf bank_mask:0xf
	v_mov_b32_dpp v167, v165 quad_perm:[1,0,3,2] row_mask:0xf bank_mask:0xf
	v_perm_b32 v168, v166, v164, v152
	v_perm_b32 v169, v167, v165, v152
	global_store_dword v[156:157], v168, off
	global_store_dword v[156:157], v169, off offset:32
	v_add_u32_e32 v154, 34, v148
	v_mad_i64_i32 v[156:157], s[62:63], v154, s96, v[150:151]
	v_mul_f32_e32 v160, 0xbfb8aa3b, v94
	v_mul_f32_e32 v161, 0xbfb8aa3b, v95
	v_mul_f32_e32 v162, 0xbfb8aa3b, v86
	v_mul_f32_e32 v163, 0xbfb8aa3b, v87
	v_exp_f32_e32 v160, v160
	v_exp_f32_e32 v161, v161
	v_exp_f32_e32 v162, v162
	v_exp_f32_e32 v163, v163
	v_add_f32_e32 v160, 1.0, v160
	v_add_f32_e32 v161, 1.0, v161
	v_add_f32_e32 v162, 1.0, v162
	v_add_f32_e32 v163, 1.0, v163
	v_rcp_f32_e32 v160, v160
	v_rcp_f32_e32 v161, v161
	v_rcp_f32_e32 v162, v162
	v_rcp_f32_e32 v163, v163
	v_mul_f32_e32 v160, v94, v160
	v_mul_f32_e32 v161, v95, v161
	v_mul_f32_e32 v162, v86, v162
	v_mul_f32_e32 v163, v87, v163
	v_mul_f32_e32 v160, v90, v160
	v_mul_f32_e32 v161, v91, v161
	v_mul_f32_e32 v162, v82, v162
	v_mul_f32_e32 v163, v83, v163
	v_cvt_pk_bf16_f32 v164, v160, v161
	v_cvt_pk_bf16_f32 v165, v162, v163
	s_nop 0
	v_mov_b32_dpp v166, v164 quad_perm:[1,0,3,2] row_mask:0xf bank_mask:0xf
	v_mov_b32_dpp v167, v165 quad_perm:[1,0,3,2] row_mask:0xf bank_mask:0xf
	v_perm_b32 v168, v166, v164, v152
	v_perm_b32 v169, v167, v165, v152
	global_store_dword v[156:157], v168, off
	global_store_dword v[156:157], v169, off offset:32
	v_add_u32_e32 v154, 48, v148
	v_mad_i64_i32 v[156:157], s[62:63], v154, s96, v[150:151]
	v_mul_f32_e32 v160, 0xbfb8aa3b, v76
	v_mul_f32_e32 v161, 0xbfb8aa3b, v77
	v_mul_f32_e32 v162, 0xbfb8aa3b, v68
	v_mul_f32_e32 v163, 0xbfb8aa3b, v69
	v_exp_f32_e32 v160, v160
	v_exp_f32_e32 v161, v161
	v_exp_f32_e32 v162, v162
	v_exp_f32_e32 v163, v163
	v_add_f32_e32 v160, 1.0, v160
	v_add_f32_e32 v161, 1.0, v161
	v_add_f32_e32 v162, 1.0, v162
	v_add_f32_e32 v163, 1.0, v163
	v_rcp_f32_e32 v160, v160
	v_rcp_f32_e32 v161, v161
	v_rcp_f32_e32 v162, v162
	v_rcp_f32_e32 v163, v163
	v_mul_f32_e32 v160, v76, v160
	v_mul_f32_e32 v161, v77, v161
	v_mul_f32_e32 v162, v68, v162
	v_mul_f32_e32 v163, v69, v163
	v_mul_f32_e32 v160, v72, v160
	v_mul_f32_e32 v161, v73, v161
	v_mul_f32_e32 v162, v64, v162
	v_mul_f32_e32 v163, v65, v163
	v_cvt_pk_bf16_f32 v164, v160, v161
	v_cvt_pk_bf16_f32 v165, v162, v163
	s_nop 0
	v_mov_b32_dpp v166, v164 quad_perm:[1,0,3,2] row_mask:0xf bank_mask:0xf
	v_mov_b32_dpp v167, v165 quad_perm:[1,0,3,2] row_mask:0xf bank_mask:0xf
	v_perm_b32 v168, v166, v164, v152
	v_perm_b32 v169, v167, v165, v152
	global_store_dword v[156:157], v168, off
	global_store_dword v[156:157], v169, off offset:32
	v_add_u32_e32 v154, 50, v148
	v_mad_i64_i32 v[156:157], s[62:63], v154, s96, v[150:151]
	v_mul_f32_e32 v160, 0xbfb8aa3b, v78
	v_mul_f32_e32 v161, 0xbfb8aa3b, v79
	v_mul_f32_e32 v162, 0xbfb8aa3b, v70
	v_mul_f32_e32 v163, 0xbfb8aa3b, v71
	v_exp_f32_e32 v160, v160
	v_exp_f32_e32 v161, v161
	v_exp_f32_e32 v162, v162
	v_exp_f32_e32 v163, v163
	v_add_f32_e32 v160, 1.0, v160
	v_add_f32_e32 v161, 1.0, v161
	v_add_f32_e32 v162, 1.0, v162
	v_add_f32_e32 v163, 1.0, v163
	v_rcp_f32_e32 v160, v160
	v_rcp_f32_e32 v161, v161
	v_rcp_f32_e32 v162, v162
	v_rcp_f32_e32 v163, v163
	v_mul_f32_e32 v160, v78, v160
	v_mul_f32_e32 v161, v79, v161
	v_mul_f32_e32 v162, v70, v162
	v_mul_f32_e32 v163, v71, v163
	v_mul_f32_e32 v160, v74, v160
	v_mul_f32_e32 v161, v75, v161
	v_mul_f32_e32 v162, v66, v162
	v_mul_f32_e32 v163, v67, v163
	v_cvt_pk_bf16_f32 v164, v160, v161
	v_cvt_pk_bf16_f32 v165, v162, v163
	s_nop 0
	v_mov_b32_dpp v166, v164 quad_perm:[1,0,3,2] row_mask:0xf bank_mask:0xf
	v_mov_b32_dpp v167, v165 quad_perm:[1,0,3,2] row_mask:0xf bank_mask:0xf
	v_perm_b32 v168, v166, v164, v152
	v_perm_b32 v169, v167, v165, v152
	global_store_dword v[156:157], v168, off
	global_store_dword v[156:157], v169, off offset:32
	v_add_u32_e32 v154, 64, v148
	v_mad_i64_i32 v[156:157], s[62:63], v154, s96, v[150:151]
	v_mul_f32_e32 v160, 0xbfb8aa3b, v60
	v_mul_f32_e32 v161, 0xbfb8aa3b, v61
; __device__ __forceinline__ u16 f2bf(float f) { return (u16)cvtpk(f, f); }
; __device__ __forceinline__ float siluf_(float x) { return x * __builtin_amdgcn_rcpf(1.f + __expf(-x)); }
; __device__ __forceinline__ void phase_ffn_in(const Params& p, int L, int f, char* lds) {
;     ...
;   auto epi_ffn = [&](int m0, int n0, auto& acc) {
;       constexpr int MIx = sizeof(acc) / sizeof(acc[0]);
;       EPI_IDX
; #pragma unroll
;       for (int mi = 0; mi < MIx; ++mi)
; #pragma unroll
;         for (int np = 0; np < 2; ++np) {
;           const int c = (((n0 + wn * 64) >> 5) + np) * 16 + l15;
; #pragma unroll
;           for (int j = 0; j < 4; ++j) {
;             const int row = m0 + wm * (MIx * 16) + mi * 16 + quad * 4 + j;
;             float a = acc[mi][2 * np][j], g = acc[mi][2 * np + 1][j];
;             hid[(size_t)row * DFF + c] = f2bf(siluf_(a) * g);
;           }
;         }
;     };
	v_mul_f32_e32 v162, 0xbfb8aa3b, v52
	v_mul_f32_e32 v163, 0xbfb8aa3b, v53
	v_exp_f32_e32 v160, v160
	v_exp_f32_e32 v161, v161
	v_exp_f32_e32 v162, v162
	v_exp_f32_e32 v163, v163
	v_add_f32_e32 v160, 1.0, v160
	v_add_f32_e32 v161, 1.0, v161
	v_add_f32_e32 v162, 1.0, v162
	v_add_f32_e32 v163, 1.0, v163
	v_rcp_f32_e32 v160, v160
	v_rcp_f32_e32 v161, v161
	v_rcp_f32_e32 v162, v162
	v_rcp_f32_e32 v163, v163
	v_mul_f32_e32 v160, v60, v160
	v_mul_f32_e32 v161, v61, v161
	v_mul_f32_e32 v162, v52, v162
	v_mul_f32_e32 v163, v53, v163
	v_mul_f32_e32 v160, v56, v160
	v_mul_f32_e32 v161, v57, v161
	v_mul_f32_e32 v162, v48, v162
	v_mul_f32_e32 v163, v49, v163
	v_cvt_pk_bf16_f32 v164, v160, v161
	v_cvt_pk_bf16_f32 v165, v162, v163
	s_nop 0
	v_mov_b32_dpp v166, v164 quad_perm:[1,0,3,2] row_mask:0xf bank_mask:0xf
	v_mov_b32_dpp v167, v165 quad_perm:[1,0,3,2] row_mask:0xf bank_mask:0xf
	v_perm_b32 v168, v166, v164, v152
	v_perm_b32 v169, v167, v165, v152
	global_store_dword v[156:157], v168, off
	global_store_dword v[156:157], v169, off offset:32
	v_add_u32_e32 v154, 66, v148
	v_mad_i64_i32 v[156:157], s[62:63], v154, s96, v[150:151]
	v_mul_f32_e32 v160, 0xbfb8aa3b, v62
	v_mul_f32_e32 v161, 0xbfb8aa3b, v63
	v_mul_f32_e32 v162, 0xbfb8aa3b, v54
	v_mul_f32_e32 v163, 0xbfb8aa3b, v55
	v_exp_f32_e32 v160, v160
	v_exp_f32_e32 v161, v161
	v_exp_f32_e32 v162, v162
	v_exp_f32_e32 v163, v163
	v_add_f32_e32 v160, 1.0, v160
	v_add_f32_e32 v161, 1.0, v161
	v_add_f32_e32 v162, 1.0, v162
	v_add_f32_e32 v163, 1.0, v163
	v_rcp_f32_e32 v160, v160
	v_rcp_f32_e32 v161, v161
	v_rcp_f32_e32 v162, v162
	v_rcp_f32_e32 v163, v163
	v_mul_f32_e32 v160, v62, v160
	v_mul_f32_e32 v161, v63, v161
	v_mul_f32_e32 v162, v54, v162
	v_mul_f32_e32 v163, v55, v163
	v_mul_f32_e32 v160, v58, v160
	v_mul_f32_e32 v161, v59, v161
	v_mul_f32_e32 v162, v50, v162
	v_mul_f32_e32 v163, v51, v163
	v_cvt_pk_bf16_f32 v164, v160, v161
	v_cvt_pk_bf16_f32 v165, v162, v163
	s_nop 0
	v_mov_b32_dpp v166, v164 quad_perm:[1,0,3,2] row_mask:0xf bank_mask:0xf
	v_mov_b32_dpp v167, v165 quad_perm:[1,0,3,2] row_mask:0xf bank_mask:0xf
	v_perm_b32 v168, v166, v164, v152
	v_perm_b32 v169, v167, v165, v152
	global_store_dword v[156:157], v168, off
	global_store_dword v[156:157], v169, off offset:32
	v_add_u32_e32 v154, 80, v148
	v_mad_i64_i32 v[156:157], s[62:63], v154, s96, v[150:151]
	v_mul_f32_e32 v160, 0xbfb8aa3b, v40
	v_mul_f32_e32 v161, 0xbfb8aa3b, v41
	v_mul_f32_e32 v162, 0xbfb8aa3b, v32
	v_mul_f32_e32 v163, 0xbfb8aa3b, v33
	v_exp_f32_e32 v160, v160
	v_exp_f32_e32 v161, v161
	v_exp_f32_e32 v162, v162
	v_exp_f32_e32 v163, v163
	v_add_f32_e32 v160, 1.0, v160
	v_add_f32_e32 v161, 1.0, v161
	v_add_f32_e32 v162, 1.0, v162
	v_add_f32_e32 v163, 1.0, v163
	v_rcp_f32_e32 v160, v160
	v_rcp_f32_e32 v161, v161
	v_rcp_f32_e32 v162, v162
	v_rcp_f32_e32 v163, v163
	v_mul_f32_e32 v160, v40, v160
	v_mul_f32_e32 v161, v41, v161
	v_mul_f32_e32 v162, v32, v162
	v_mul_f32_e32 v163, v33, v163
	v_mul_f32_e32 v160, v44, v160
	v_mul_f32_e32 v161, v45, v161
	v_mul_f32_e32 v162, v36, v162
	v_mul_f32_e32 v163, v37, v163
	v_cvt_pk_bf16_f32 v164, v160, v161
	v_cvt_pk_bf16_f32 v165, v162, v163
	s_nop 0
	v_mov_b32_dpp v166, v164 quad_perm:[1,0,3,2] row_mask:0xf bank_mask:0xf
	v_mov_b32_dpp v167, v165 quad_perm:[1,0,3,2] row_mask:0xf bank_mask:0xf
	v_perm_b32 v168, v166, v164, v152
	v_perm_b32 v169, v167, v165, v152
	global_store_dword v[156:157], v168, off
	global_store_dword v[156:157], v169, off offset:32
	v_add_u32_e32 v154, 82, v148
	v_mad_i64_i32 v[156:157], s[62:63], v154, s96, v[150:151]
	v_mul_f32_e32 v160, 0xbfb8aa3b, v42
	v_mul_f32_e32 v161, 0xbfb8aa3b, v43
	v_mul_f32_e32 v162, 0xbfb8aa3b, v34
	v_mul_f32_e32 v163, 0xbfb8aa3b, v35
	v_exp_f32_e32 v160, v160
	v_exp_f32_e32 v161, v161
	v_exp_f32_e32 v162, v162
	v_exp_f32_e32 v163, v163
	v_add_f32_e32 v160, 1.0, v160
	v_add_f32_e32 v161, 1.0, v161
	v_add_f32_e32 v162, 1.0, v162
	v_add_f32_e32 v163, 1.0, v163
	v_rcp_f32_e32 v160, v160
	v_rcp_f32_e32 v161, v161
	v_rcp_f32_e32 v162, v162
	v_rcp_f32_e32 v163, v163
	v_mul_f32_e32 v160, v42, v160
	v_mul_f32_e32 v161, v43, v161
	v_mul_f32_e32 v162, v34, v162
	v_mul_f32_e32 v163, v35, v163
	v_mul_f32_e32 v160, v46, v160
	v_mul_f32_e32 v161, v47, v161
	v_mul_f32_e32 v162, v38, v162
	v_mul_f32_e32 v163, v39, v163
	v_cvt_pk_bf16_f32 v164, v160, v161
	v_cvt_pk_bf16_f32 v165, v162, v163
	s_nop 0
	v_mov_b32_dpp v166, v164 quad_perm:[1,0,3,2] row_mask:0xf bank_mask:0xf
	v_mov_b32_dpp v167, v165 quad_perm:[1,0,3,2] row_mask:0xf bank_mask:0xf
	v_perm_b32 v168, v166, v164, v152
	v_perm_b32 v169, v167, v165, v152
	global_store_dword v[156:157], v168, off
	global_store_dword v[156:157], v169, off offset:32
	v_add_u32_e32 v154, 96, v148
	v_mad_i64_i32 v[156:157], s[62:63], v154, s96, v[150:151]
; __device__ __forceinline__ u16 f2bf(float f) { return (u16)cvtpk(f, f); }
; __device__ __forceinline__ float siluf_(float x) { return x * __builtin_amdgcn_rcpf(1.f + __expf(-x)); }
; __device__ __forceinline__ void phase_ffn_in(const Params& p, int L, int f, char* lds) {
;     ...
;   auto epi_ffn = [&](int m0, int n0, auto& acc) {
;       constexpr int MIx = sizeof(acc) / sizeof(acc[0]);
;       EPI_IDX
; #pragma unroll
;       for (int mi = 0; mi < MIx; ++mi)
; #pragma unroll
;         for (int np = 0; np < 2; ++np) {
;           const int c = (((n0 + wn * 64) >> 5) + np) * 16 + l15;
; #pragma unroll
;           for (int j = 0; j < 4; ++j) {
;             const int row = m0 + wm * (MIx * 16) + mi * 16 + quad * 4 + j;
;             float a = acc[mi][2 * np][j], g = acc[mi][2 * np + 1][j];
;             hid[(size_t)row * DFF + c] = f2bf(siluf_(a) * g);
;           }
;         }
;     };
	v_mul_f32_e32 v160, 0xbfb8aa3b, v24
	v_mul_f32_e32 v161, 0xbfb8aa3b, v25
	v_mul_f32_e32 v162, 0xbfb8aa3b, v16
	v_mul_f32_e32 v163, 0xbfb8aa3b, v17
	v_exp_f32_e32 v160, v160
	v_exp_f32_e32 v161, v161
	v_exp_f32_e32 v162, v162
	v_exp_f32_e32 v163, v163
	v_add_f32_e32 v160, 1.0, v160
	v_add_f32_e32 v161, 1.0, v161
	v_add_f32_e32 v162, 1.0, v162
	v_add_f32_e32 v163, 1.0, v163
	v_rcp_f32_e32 v160, v160
	v_rcp_f32_e32 v161, v161
	v_rcp_f32_e32 v162, v162
	v_rcp_f32_e32 v163, v163
	v_mul_f32_e32 v160, v24, v160
	v_mul_f32_e32 v161, v25, v161
	v_mul_f32_e32 v162, v16, v162
	v_mul_f32_e32 v163, v17, v163
	v_mul_f32_e32 v160, v28, v160
	v_mul_f32_e32 v161, v29, v161
	v_mul_f32_e32 v162, v20, v162
	v_mul_f32_e32 v163, v21, v163
	v_cvt_pk_bf16_f32 v164, v160, v161
	v_cvt_pk_bf16_f32 v165, v162, v163
	s_nop 0
	v_mov_b32_dpp v166, v164 quad_perm:[1,0,3,2] row_mask:0xf bank_mask:0xf
	v_mov_b32_dpp v167, v165 quad_perm:[1,0,3,2] row_mask:0xf bank_mask:0xf
	v_perm_b32 v168, v166, v164, v152
	v_perm_b32 v169, v167, v165, v152
	global_store_dword v[156:157], v168, off
	global_store_dword v[156:157], v169, off offset:32
	v_add_u32_e32 v154, 98, v148
	v_mad_i64_i32 v[156:157], s[62:63], v154, s96, v[150:151]
	v_mul_f32_e32 v160, 0xbfb8aa3b, v26
	v_mul_f32_e32 v161, 0xbfb8aa3b, v27
	v_mul_f32_e32 v162, 0xbfb8aa3b, v18
	v_mul_f32_e32 v163, 0xbfb8aa3b, v19
	v_exp_f32_e32 v160, v160
	v_exp_f32_e32 v161, v161
	v_exp_f32_e32 v162, v162
	v_exp_f32_e32 v163, v163
	v_add_f32_e32 v160, 1.0, v160
	v_add_f32_e32 v161, 1.0, v161
	v_add_f32_e32 v162, 1.0, v162
	v_add_f32_e32 v163, 1.0, v163
	v_rcp_f32_e32 v160, v160
	v_rcp_f32_e32 v161, v161
	v_rcp_f32_e32 v162, v162
	v_rcp_f32_e32 v163, v163
	v_mul_f32_e32 v160, v26, v160
	v_mul_f32_e32 v161, v27, v161
	v_mul_f32_e32 v162, v18, v162
	v_mul_f32_e32 v163, v19, v163
	v_mul_f32_e32 v160, v30, v160
	v_mul_f32_e32 v161, v31, v161
	v_mul_f32_e32 v162, v22, v162
	v_mul_f32_e32 v163, v23, v163
	v_cvt_pk_bf16_f32 v164, v160, v161
	v_cvt_pk_bf16_f32 v165, v162, v163
	s_nop 0
	v_mov_b32_dpp v166, v164 quad_perm:[1,0,3,2] row_mask:0xf bank_mask:0xf
	v_mov_b32_dpp v167, v165 quad_perm:[1,0,3,2] row_mask:0xf bank_mask:0xf
	v_perm_b32 v168, v166, v164, v152
	v_perm_b32 v169, v167, v165, v152
	global_store_dword v[156:157], v168, off
	global_store_dword v[156:157], v169, off offset:32
	v_add_u32_e32 v154, 112, v148
	v_mad_i64_i32 v[156:157], s[62:63], v154, s96, v[150:151]
	v_mul_f32_e32 v160, 0xbfb8aa3b, v8
	v_mul_f32_e32 v161, 0xbfb8aa3b, v9
	v_mul_f32_e32 v162, 0xbfb8aa3b, v0
	v_mul_f32_e32 v163, 0xbfb8aa3b, v1
	v_exp_f32_e32 v160, v160
	v_exp_f32_e32 v161, v161
	v_exp_f32_e32 v162, v162
	v_exp_f32_e32 v163, v163
	v_add_f32_e32 v160, 1.0, v160
	v_add_f32_e32 v161, 1.0, v161
	v_add_f32_e32 v162, 1.0, v162
	v_add_f32_e32 v163, 1.0, v163
	v_rcp_f32_e32 v160, v160
	v_rcp_f32_e32 v161, v161
	v_rcp_f32_e32 v162, v162
	v_rcp_f32_e32 v163, v163
	v_mul_f32_e32 v160, v8, v160
	v_mul_f32_e32 v161, v9, v161
	v_mul_f32_e32 v162, v0, v162
	v_mul_f32_e32 v163, v1, v163
	v_mul_f32_e32 v160, v12, v160
	v_mul_f32_e32 v161, v13, v161
	v_mul_f32_e32 v162, v4, v162
	v_mul_f32_e32 v163, v5, v163
	v_cvt_pk_bf16_f32 v164, v160, v161
	v_cvt_pk_bf16_f32 v165, v162, v163
	s_nop 0
	v_mov_b32_dpp v166, v164 quad_perm:[1,0,3,2] row_mask:0xf bank_mask:0xf
	v_mov_b32_dpp v167, v165 quad_perm:[1,0,3,2] row_mask:0xf bank_mask:0xf
	v_perm_b32 v168, v166, v164, v152
	v_perm_b32 v169, v167, v165, v152
	global_store_dword v[156:157], v168, off
	global_store_dword v[156:157], v169, off offset:32
	v_add_u32_e32 v154, 114, v148
	v_mad_i64_i32 v[156:157], s[62:63], v154, s96, v[150:151]
	v_mul_f32_e32 v160, 0xbfb8aa3b, v10
	v_mul_f32_e32 v161, 0xbfb8aa3b, v11
	v_mul_f32_e32 v162, 0xbfb8aa3b, v2
	v_mul_f32_e32 v163, 0xbfb8aa3b, v3
	v_exp_f32_e32 v160, v160
	v_exp_f32_e32 v161, v161
	v_exp_f32_e32 v162, v162
	v_exp_f32_e32 v163, v163
	v_add_f32_e32 v160, 1.0, v160
	v_add_f32_e32 v161, 1.0, v161
	v_add_f32_e32 v162, 1.0, v162
	v_add_f32_e32 v163, 1.0, v163
	v_rcp_f32_e32 v160, v160
	v_rcp_f32_e32 v161, v161
	v_rcp_f32_e32 v162, v162
	v_rcp_f32_e32 v163, v163
	v_mul_f32_e32 v160, v10, v160
	v_mul_f32_e32 v161, v11, v161
	v_mul_f32_e32 v162, v2, v162
	v_mul_f32_e32 v163, v3, v163
	v_mul_f32_e32 v160, v14, v160
	v_mul_f32_e32 v161, v15, v161
	v_mul_f32_e32 v162, v6, v162
	v_mul_f32_e32 v163, v7, v163
	v_cvt_pk_bf16_f32 v164, v160, v161
	v_cvt_pk_bf16_f32 v165, v162, v163
	s_nop 0
	v_mov_b32_dpp v166, v164 quad_perm:[1,0,3,2] row_mask:0xf bank_mask:0xf
	v_mov_b32_dpp v167, v165 quad_perm:[1,0,3,2] row_mask:0xf bank_mask:0xf
	v_perm_b32 v168, v166, v164, v152
	v_perm_b32 v169, v167, v165, v152
	global_store_dword v[156:157], v168, off
	global_store_dword v[156:157], v169, off offset:32
	s_cbranch_scc1 .LBB0_212
